# EpiResid phases: all stores write-through (sc1) and the XCD leader's L2 writeback dropped at those five grid barriers
# speedup vs baseline: 1.0004x; 1.0004x over previous
.LBB0_461:
	s_andn2_saveexec_b64 s[4:5], s[4:5]
	s_cbranch_execz .LBB0_481
	s_mov_b64 s[4:5], exec
	s_waitcnt lgkmcnt(0)
	s_waitcnt vmcnt(0)
	v_mbcnt_lo_u32_b32 v1, s4, 0
	v_mbcnt_hi_u32_b32 v1, s5, v1
	v_cmp_eq_u32_e32 vcc, 0, v1
	s_and_saveexec_b64 s[6:7], vcc
	s_cbranch_execz .LBB0_464
	s_bcnt1_i32_b64 s4, s[4:5]
	v_mov_b32_e32 v2, 0x4c3000
	v_mov_b32_e32 v3, s4
	global_atomic_add v2, v2, v3, s[94:95] offset:1024 sc0

.LBB0_1224:
	s_andn2_saveexec_b64 s[4:5], s[4:5]
	s_cbranch_execz .LBB0_1244
	s_mov_b64 s[4:5], exec
	s_waitcnt lgkmcnt(0)
	s_waitcnt vmcnt(0)
	v_mbcnt_lo_u32_b32 v1, s4, 0
	v_mbcnt_hi_u32_b32 v1, s5, v1
	v_cmp_eq_u32_e32 vcc, 0, v1
	s_and_saveexec_b64 s[6:7], vcc
	s_cbranch_execz .LBB0_1227
	s_bcnt1_i32_b64 s4, s[4:5]
	v_mov_b32_e32 v2, 0x4c3000
	v_mov_b32_e32 v3, s4
	global_atomic_add v2, v2, v3, s[88:89] offset:1024 sc0

.LBB0_2411:
	s_andn2_saveexec_b64 s[4:5], s[4:5]
	s_cbranch_execz .LBB0_2431
	s_mov_b64 s[4:5], exec
	s_waitcnt lgkmcnt(0)
	s_waitcnt vmcnt(0)
	v_mbcnt_lo_u32_b32 v1, s4, 0
	v_mbcnt_hi_u32_b32 v1, s5, v1
	v_cmp_eq_u32_e32 vcc, 0, v1
	s_and_saveexec_b64 s[6:7], vcc
	s_cbranch_execz .LBB0_2414
	s_bcnt1_i32_b64 s4, s[4:5]
	v_mov_b32_e32 v2, 0x4c3000
	v_mov_b32_e32 v3, s4
	global_atomic_add v2, v2, v3, s[84:85] offset:1024 sc0
